# v32
# baseline (speedup 1.0000x reference)
.LBB0_188:
	v_mov_b64_e32 v[0:1], s[10:11]
	s_ashr_i32 s25, s24, 31
	v_cmp_lt_i64_e32 vcc, s[26:27], v[0:1]
	s_lshl_b64 s[26:27], s[24:25], 19
	s_add_u32 s26, s16, s26
	s_addc_u32 s27, s17, s27
	s_and_b64 s[28:29], vcc, exec
	s_cselect_b32 s25, s27, s35
	s_cselect_b32 s69, s26, s34
	s_ashr_i32 s23, s22, 31
	s_lshl_b64 s[28:29], s[22:23], 19
	s_add_u32 s28, s18, s28
	s_addc_u32 s29, s19, s29
	s_and_b64 s[38:39], vcc, exec
	s_cselect_b32 s23, s29, s37
	s_cselect_b32 s70, s28, s36
	s_add_u32 s34, s34, 0x40080
	s_addc_u32 s35, s35, 0
	s_add_u32 s71, s36, 0x100
	v_mov_b32_e32 v0, 0
	s_addc_u32 s73, s37, 0
	s_mov_b32 s74, -2
	v_mov_b32_e32 v1, v0
	v_mov_b32_e32 v2, v0
	v_mov_b32_e32 v3, v0
	v_mov_b32_e32 v4, v0
	v_mov_b32_e32 v5, v0
	v_mov_b32_e32 v6, v0
	v_mov_b32_e32 v7, v0
	v_mov_b32_e32 v8, v0
	v_mov_b32_e32 v9, v0
	v_mov_b32_e32 v10, v0
	v_mov_b32_e32 v11, v0
	v_mov_b32_e32 v16, v0
	v_mov_b32_e32 v17, v0
	v_mov_b32_e32 v18, v0
	v_mov_b32_e32 v19, v0
	v_mov_b32_e32 v24, v0
	v_mov_b32_e32 v25, v0
	v_mov_b32_e32 v26, v0
	v_mov_b32_e32 v27, v0
	v_mov_b32_e32 v32, v0
	v_mov_b32_e32 v33, v0
	v_mov_b32_e32 v34, v0
	v_mov_b32_e32 v35, v0
	v_mov_b32_e32 v40, v0
	v_mov_b32_e32 v41, v0
	v_mov_b32_e32 v42, v0
	v_mov_b32_e32 v43, v0
	v_mov_b32_e32 v48, v0
	v_mov_b32_e32 v49, v0
	v_mov_b32_e32 v50, v0
	v_mov_b32_e32 v51, v0
	v_mov_b32_e32 v12, v0
	v_mov_b32_e32 v13, v0
	v_mov_b32_e32 v14, v0
	v_mov_b32_e32 v15, v0
	v_mov_b32_e32 v20, v0
	v_mov_b32_e32 v21, v0
	v_mov_b32_e32 v22, v0
	v_mov_b32_e32 v23, v0
	v_mov_b32_e32 v28, v0
	v_mov_b32_e32 v29, v0
	v_mov_b32_e32 v30, v0
	v_mov_b32_e32 v31, v0
	v_mov_b32_e32 v36, v0
	v_mov_b32_e32 v37, v0
	v_mov_b32_e32 v38, v0
	v_mov_b32_e32 v39, v0
	v_mov_b32_e32 v44, v0
	v_mov_b32_e32 v45, v0
	v_mov_b32_e32 v46, v0
	v_mov_b32_e32 v47, v0
	v_mov_b32_e32 v52, v0
	v_mov_b32_e32 v53, v0
	v_mov_b32_e32 v54, v0
	v_mov_b32_e32 v55, v0
	v_mov_b32_e32 v56, v0
	v_mov_b32_e32 v57, v0
	v_mov_b32_e32 v58, v0
	v_mov_b32_e32 v59, v0
	v_mov_b32_e32 v60, v0
	v_mov_b32_e32 v61, v0
	v_mov_b32_e32 v62, v0
	v_mov_b32_e32 v63, v0
	v_mov_b32_e32 v64, v0
	v_mov_b32_e32 v65, v0
	v_mov_b32_e32 v66, v0
	v_mov_b32_e32 v67, v0
	v_mov_b32_e32 v68, v0
	v_mov_b32_e32 v69, v0
	v_mov_b32_e32 v70, v0
	v_mov_b32_e32 v71, v0
	v_mov_b32_e32 v72, v0
	v_mov_b32_e32 v73, v0
	v_mov_b32_e32 v74, v0
	v_mov_b32_e32 v75, v0
	v_mov_b32_e32 v80, v0
	v_mov_b32_e32 v81, v0
	v_mov_b32_e32 v82, v0
	v_mov_b32_e32 v83, v0
	v_mov_b32_e32 v88, v0
	v_mov_b32_e32 v89, v0
	v_mov_b32_e32 v90, v0
	v_mov_b32_e32 v91, v0
	v_mov_b32_e32 v96, v0
	v_mov_b32_e32 v97, v0
	v_mov_b32_e32 v98, v0
	v_mov_b32_e32 v99, v0
	v_mov_b32_e32 v104, v0
	v_mov_b32_e32 v105, v0
	v_mov_b32_e32 v106, v0
	v_mov_b32_e32 v107, v0
	v_mov_b32_e32 v112, v0
	v_mov_b32_e32 v113, v0
	v_mov_b32_e32 v114, v0
	v_mov_b32_e32 v115, v0
	v_mov_b32_e32 v76, v0
	v_mov_b32_e32 v77, v0
	v_mov_b32_e32 v78, v0
	v_mov_b32_e32 v79, v0
	v_mov_b32_e32 v84, v0
	v_mov_b32_e32 v85, v0
	v_mov_b32_e32 v86, v0
	v_mov_b32_e32 v87, v0
	v_mov_b32_e32 v92, v0
	v_mov_b32_e32 v93, v0
	v_mov_b32_e32 v94, v0
	v_mov_b32_e32 v95, v0
	v_mov_b32_e32 v100, v0
	v_mov_b32_e32 v101, v0
	v_mov_b32_e32 v102, v0
	v_mov_b32_e32 v103, v0
	v_mov_b32_e32 v108, v0
	v_mov_b32_e32 v109, v0
	v_mov_b32_e32 v110, v0
	v_mov_b32_e32 v111, v0
	v_mov_b32_e32 v116, v0
	v_mov_b32_e32 v117, v0
	v_mov_b32_e32 v118, v0
	v_mov_b32_e32 v119, v0
	v_mov_b32_e32 v120, v0
	v_mov_b32_e32 v121, v0
	v_mov_b32_e32 v122, v0
	v_mov_b32_e32 v123, v0
	v_mov_b32_e32 v124, v0
	v_mov_b32_e32 v125, v0
	v_mov_b32_e32 v126, v0
	v_mov_b32_e32 v127, v0
	.p2align 6

.LBB0_202:
	s_ashr_i32 s17, s16, 31
	v_cmp_lt_i64_e32 vcc, s[18:19], v[140:141]
	s_lshl_b64 s[18:19], s[16:17], 19
	s_add_u32 s18, s31, s18
	s_addc_u32 s19, s34, s19
	s_and_b64 s[20:21], vcc, exec
	s_cselect_b32 s5, s19, s25
	s_cselect_b32 s17, s18, s24
	s_ashr_i32 s15, s14, 31
	s_lshl_b64 s[20:21], s[14:15], 19
	s_add_u32 s20, s8, s20
	s_addc_u32 s21, s9, s21
	s_and_b64 s[28:29], vcc, exec
	s_cselect_b32 s15, s21, s27
	s_cselect_b32 s23, s20, s26
	s_add_u32 s24, s24, 0x40080
	s_addc_u32 s25, s25, 0
	s_add_u32 s52, s26, 0x100
	v_mov_b32_e32 v0, 0
	s_addc_u32 s53, s27, 0
	s_mov_b32 s54, -2
	v_mov_b32_e32 v1, v0
	v_mov_b32_e32 v2, v0
	v_mov_b32_e32 v3, v0
	v_mov_b32_e32 v4, v0
	v_mov_b32_e32 v5, v0
	v_mov_b32_e32 v6, v0
	v_mov_b32_e32 v7, v0
	v_mov_b32_e32 v16, v0
	v_mov_b32_e32 v17, v0
	v_mov_b32_e32 v18, v0
	v_mov_b32_e32 v19, v0
	v_mov_b32_e32 v20, v0
	v_mov_b32_e32 v21, v0
	v_mov_b32_e32 v22, v0
	v_mov_b32_e32 v23, v0
	v_mov_b32_e32 v32, v0
	v_mov_b32_e32 v33, v0
	v_mov_b32_e32 v34, v0
	v_mov_b32_e32 v35, v0
	v_mov_b32_e32 v36, v0
	v_mov_b32_e32 v37, v0
	v_mov_b32_e32 v38, v0
	v_mov_b32_e32 v39, v0
	v_mov_b32_e32 v48, v0
	v_mov_b32_e32 v49, v0
	v_mov_b32_e32 v50, v0
	v_mov_b32_e32 v51, v0
	v_mov_b32_e32 v52, v0
	v_mov_b32_e32 v53, v0
	v_mov_b32_e32 v54, v0
	v_mov_b32_e32 v55, v0
	v_mov_b32_e32 v8, v0
	v_mov_b32_e32 v9, v0
	v_mov_b32_e32 v10, v0
	v_mov_b32_e32 v11, v0
	v_mov_b32_e32 v12, v0
	v_mov_b32_e32 v13, v0
	v_mov_b32_e32 v14, v0
	v_mov_b32_e32 v15, v0
	v_mov_b32_e32 v24, v0
	v_mov_b32_e32 v25, v0
	v_mov_b32_e32 v26, v0
	v_mov_b32_e32 v27, v0
	v_mov_b32_e32 v28, v0
	v_mov_b32_e32 v29, v0
	v_mov_b32_e32 v30, v0
	v_mov_b32_e32 v31, v0
	v_mov_b32_e32 v40, v0
	v_mov_b32_e32 v41, v0
	v_mov_b32_e32 v42, v0
	v_mov_b32_e32 v43, v0
	v_mov_b32_e32 v44, v0
	v_mov_b32_e32 v45, v0
	v_mov_b32_e32 v46, v0
	v_mov_b32_e32 v47, v0
	v_mov_b32_e32 v56, v0
	v_mov_b32_e32 v57, v0
	v_mov_b32_e32 v58, v0
	v_mov_b32_e32 v59, v0
	v_mov_b32_e32 v60, v0
	v_mov_b32_e32 v61, v0
	v_mov_b32_e32 v62, v0
	v_mov_b32_e32 v63, v0
	v_mov_b32_e32 v64, v0
	v_mov_b32_e32 v65, v0
	v_mov_b32_e32 v66, v0
	v_mov_b32_e32 v67, v0
	v_mov_b32_e32 v68, v0
	v_mov_b32_e32 v69, v0
	v_mov_b32_e32 v70, v0
	v_mov_b32_e32 v71, v0
	v_mov_b32_e32 v80, v0
	v_mov_b32_e32 v81, v0
	v_mov_b32_e32 v82, v0
	v_mov_b32_e32 v83, v0
	v_mov_b32_e32 v84, v0
	v_mov_b32_e32 v85, v0
	v_mov_b32_e32 v86, v0
	v_mov_b32_e32 v87, v0
	v_mov_b32_e32 v96, v0
	v_mov_b32_e32 v97, v0
	v_mov_b32_e32 v98, v0
	v_mov_b32_e32 v99, v0
	v_mov_b32_e32 v100, v0
	v_mov_b32_e32 v101, v0
	v_mov_b32_e32 v102, v0
	v_mov_b32_e32 v103, v0
	v_mov_b32_e32 v112, v0
	v_mov_b32_e32 v113, v0
	v_mov_b32_e32 v114, v0
	v_mov_b32_e32 v115, v0
	v_mov_b32_e32 v116, v0
	v_mov_b32_e32 v117, v0
	v_mov_b32_e32 v118, v0
	v_mov_b32_e32 v119, v0
	v_mov_b32_e32 v72, v0
	v_mov_b32_e32 v73, v0
	v_mov_b32_e32 v74, v0
	v_mov_b32_e32 v75, v0
	v_mov_b32_e32 v76, v0
	v_mov_b32_e32 v77, v0
	v_mov_b32_e32 v78, v0
	v_mov_b32_e32 v79, v0
	v_mov_b32_e32 v88, v0
	v_mov_b32_e32 v89, v0
	v_mov_b32_e32 v90, v0
	v_mov_b32_e32 v91, v0
	v_mov_b32_e32 v92, v0
	v_mov_b32_e32 v93, v0
	v_mov_b32_e32 v94, v0
	v_mov_b32_e32 v95, v0
	v_mov_b32_e32 v104, v0
	v_mov_b32_e32 v105, v0
	v_mov_b32_e32 v106, v0
	v_mov_b32_e32 v107, v0
	v_mov_b32_e32 v108, v0
	v_mov_b32_e32 v109, v0
	v_mov_b32_e32 v110, v0
	v_mov_b32_e32 v111, v0
	v_mov_b32_e32 v120, v0
	v_mov_b32_e32 v121, v0
	v_mov_b32_e32 v122, v0
	v_mov_b32_e32 v123, v0
	v_mov_b32_e32 v124, v0
	v_mov_b32_e32 v125, v0
	v_mov_b32_e32 v126, v0
	v_mov_b32_e32 v127, v0
	.p2align 6

.LBB0_320:
	s_add_u32 s35, s10, 0x100
	v_mov_b32_e32 v0, 0
	s_addc_u32 s37, s11, 0
	s_mov_b32 s60, -2
	v_mov_b32_e32 v1, v0
	v_mov_b32_e32 v2, v0
	v_mov_b32_e32 v3, v0
	v_mov_b32_e32 v4, v0
	v_mov_b32_e32 v5, v0
	v_mov_b32_e32 v6, v0
	v_mov_b32_e32 v7, v0
	v_mov_b32_e32 v8, v0
	v_mov_b32_e32 v9, v0
	v_mov_b32_e32 v10, v0
	v_mov_b32_e32 v11, v0
	v_mov_b32_e32 v12, v0
	v_mov_b32_e32 v13, v0
	v_mov_b32_e32 v14, v0
	v_mov_b32_e32 v15, v0
	v_mov_b32_e32 v16, v0
	v_mov_b32_e32 v17, v0
	v_mov_b32_e32 v18, v0
	v_mov_b32_e32 v19, v0
	v_mov_b32_e32 v20, v0
	v_mov_b32_e32 v21, v0
	v_mov_b32_e32 v22, v0
	v_mov_b32_e32 v23, v0
	v_mov_b32_e32 v24, v0
	v_mov_b32_e32 v25, v0
	v_mov_b32_e32 v26, v0
	v_mov_b32_e32 v27, v0
	v_mov_b32_e32 v28, v0
	v_mov_b32_e32 v29, v0
	v_mov_b32_e32 v30, v0
	v_mov_b32_e32 v31, v0
	v_mov_b32_e32 v64, v0
	v_mov_b32_e32 v65, v0
	v_mov_b32_e32 v66, v0
	v_mov_b32_e32 v67, v0
	v_mov_b32_e32 v68, v0
	v_mov_b32_e32 v69, v0
	v_mov_b32_e32 v70, v0
	v_mov_b32_e32 v71, v0
	v_mov_b32_e32 v72, v0
	v_mov_b32_e32 v73, v0
	v_mov_b32_e32 v74, v0
	v_mov_b32_e32 v75, v0
	v_mov_b32_e32 v76, v0
	v_mov_b32_e32 v77, v0
	v_mov_b32_e32 v78, v0
	v_mov_b32_e32 v79, v0
	v_mov_b32_e32 v80, v0
	v_mov_b32_e32 v81, v0
	v_mov_b32_e32 v82, v0
	v_mov_b32_e32 v83, v0
	v_mov_b32_e32 v84, v0
	v_mov_b32_e32 v85, v0
	v_mov_b32_e32 v86, v0
	v_mov_b32_e32 v87, v0
	v_mov_b32_e32 v88, v0
	v_mov_b32_e32 v89, v0
	v_mov_b32_e32 v90, v0
	v_mov_b32_e32 v91, v0
	v_mov_b32_e32 v92, v0
	v_mov_b32_e32 v93, v0
	v_mov_b32_e32 v94, v0
	v_mov_b32_e32 v95, v0
	v_mov_b32_e32 v32, v0
	v_mov_b32_e32 v33, v0
	v_mov_b32_e32 v34, v0
	v_mov_b32_e32 v35, v0
	v_mov_b32_e32 v36, v0
	v_mov_b32_e32 v37, v0
	v_mov_b32_e32 v38, v0
	v_mov_b32_e32 v39, v0
	v_mov_b32_e32 v40, v0
	v_mov_b32_e32 v41, v0
	v_mov_b32_e32 v42, v0
	v_mov_b32_e32 v43, v0
	v_mov_b32_e32 v44, v0
	v_mov_b32_e32 v45, v0
	v_mov_b32_e32 v46, v0
	v_mov_b32_e32 v47, v0
	v_mov_b32_e32 v48, v0
	v_mov_b32_e32 v49, v0
	v_mov_b32_e32 v50, v0
	v_mov_b32_e32 v51, v0
	v_mov_b32_e32 v52, v0
	v_mov_b32_e32 v53, v0
	v_mov_b32_e32 v54, v0
	v_mov_b32_e32 v55, v0
	v_mov_b32_e32 v56, v0
	v_mov_b32_e32 v57, v0
	v_mov_b32_e32 v58, v0
	v_mov_b32_e32 v59, v0
	v_mov_b32_e32 v60, v0
	v_mov_b32_e32 v61, v0
	v_mov_b32_e32 v62, v0
	v_mov_b32_e32 v63, v0
	v_mov_b32_e32 v96, v0
	v_mov_b32_e32 v97, v0
	v_mov_b32_e32 v98, v0
	v_mov_b32_e32 v99, v0
	v_mov_b32_e32 v100, v0
	v_mov_b32_e32 v101, v0
	v_mov_b32_e32 v102, v0
	v_mov_b32_e32 v103, v0
	v_mov_b32_e32 v104, v0
	v_mov_b32_e32 v105, v0
	v_mov_b32_e32 v106, v0
	v_mov_b32_e32 v107, v0
	v_mov_b32_e32 v108, v0
	v_mov_b32_e32 v109, v0
	v_mov_b32_e32 v110, v0
	v_mov_b32_e32 v111, v0
	v_mov_b32_e32 v112, v0
	v_mov_b32_e32 v113, v0
	v_mov_b32_e32 v114, v0
	v_mov_b32_e32 v115, v0
	v_mov_b32_e32 v116, v0
	v_mov_b32_e32 v117, v0
	v_mov_b32_e32 v118, v0
	v_mov_b32_e32 v119, v0
	v_mov_b32_e32 v120, v0
	v_mov_b32_e32 v121, v0
	v_mov_b32_e32 v122, v0
	v_mov_b32_e32 v123, v0
	v_mov_b32_e32 v124, v0
	v_mov_b32_e32 v125, v0
	v_mov_b32_e32 v126, v0
	v_mov_b32_e32 v127, v0
	.p2align 6

.LBB0_582:
	s_ashr_i32 s29, s28, 31
	v_cmp_lt_i64_e32 vcc, s[30:31], v[148:149]
	s_lshl_b64 s[30:31], s[28:29], 19
	s_add_u32 s30, s44, s30
	s_addc_u32 s31, s46, s31
	s_and_b64 s[34:35], vcc, exec
	s_cselect_b32 s9, s31, s37
	s_cselect_b32 s29, s30, s36
	s_ashr_i32 s27, s26, 31
	s_lshl_b64 s[34:35], s[26:27], 19
	s_add_u32 s34, s47, s34
	s_addc_u32 s35, s48, s35
	s_and_b64 s[40:41], vcc, exec
	s_cselect_b32 s27, s35, s39
	s_cselect_b32 s60, s34, s38
	s_add_u32 s36, s36, 0x40080
	s_addc_u32 s37, s37, 0
	s_add_u32 s61, s38, 0x100
	v_mov_b32_e32 v0, 0
	s_addc_u32 s62, s39, 0
	s_mov_b32 s63, -2
	s_waitcnt lgkmcnt(0)
	v_mov_b32_e32 v1, v0
	v_mov_b32_e32 v2, v0
	v_mov_b32_e32 v3, v0
	v_mov_b32_e32 v4, v0
	v_mov_b32_e32 v5, v0
	v_mov_b32_e32 v6, v0
	v_mov_b32_e32 v7, v0
	v_mov_b32_e32 v20, v0
	v_mov_b32_e32 v21, v0
	v_mov_b32_e32 v22, v0
	v_mov_b32_e32 v23, v0
	v_mov_b32_e32 v16, v0
	v_mov_b32_e32 v17, v0
	v_mov_b32_e32 v18, v0
	v_mov_b32_e32 v19, v0
	v_mov_b32_e32 v36, v0
	v_mov_b32_e32 v37, v0
	v_mov_b32_e32 v38, v0
	v_mov_b32_e32 v39, v0
	v_mov_b32_e32 v32, v0
	v_mov_b32_e32 v33, v0
	v_mov_b32_e32 v34, v0
	v_mov_b32_e32 v35, v0
	v_mov_b32_e32 v52, v0
	v_mov_b32_e32 v53, v0
	v_mov_b32_e32 v54, v0
	v_mov_b32_e32 v55, v0
	v_mov_b32_e32 v48, v0
	v_mov_b32_e32 v49, v0
	v_mov_b32_e32 v50, v0
	v_mov_b32_e32 v51, v0
	v_mov_b32_e32 v12, v0
	v_mov_b32_e32 v13, v0
	v_mov_b32_e32 v14, v0
	v_mov_b32_e32 v15, v0
	v_mov_b32_e32 v8, v0
	v_mov_b32_e32 v9, v0
	v_mov_b32_e32 v10, v0
	v_mov_b32_e32 v11, v0
	v_mov_b32_e32 v28, v0
	v_mov_b32_e32 v29, v0
	v_mov_b32_e32 v30, v0
	v_mov_b32_e32 v31, v0
	v_mov_b32_e32 v24, v0
	v_mov_b32_e32 v25, v0
	v_mov_b32_e32 v26, v0
	v_mov_b32_e32 v27, v0
	v_mov_b32_e32 v44, v0
	v_mov_b32_e32 v45, v0
	v_mov_b32_e32 v46, v0
	v_mov_b32_e32 v47, v0
	v_mov_b32_e32 v40, v0
	v_mov_b32_e32 v41, v0
	v_mov_b32_e32 v42, v0
	v_mov_b32_e32 v43, v0
	v_mov_b32_e32 v60, v0
	v_mov_b32_e32 v61, v0
	v_mov_b32_e32 v62, v0
	v_mov_b32_e32 v63, v0
	v_mov_b32_e32 v56, v0
	v_mov_b32_e32 v57, v0
	v_mov_b32_e32 v58, v0
	v_mov_b32_e32 v59, v0
	v_mov_b32_e32 v68, v0
	v_mov_b32_e32 v69, v0
	v_mov_b32_e32 v70, v0
	v_mov_b32_e32 v71, v0
	v_mov_b32_e32 v64, v0
	v_mov_b32_e32 v65, v0
	v_mov_b32_e32 v66, v0
	v_mov_b32_e32 v67, v0
	v_mov_b32_e32 v84, v0
	v_mov_b32_e32 v85, v0
	v_mov_b32_e32 v86, v0
	v_mov_b32_e32 v87, v0
	v_mov_b32_e32 v80, v0
	v_mov_b32_e32 v81, v0
	v_mov_b32_e32 v82, v0
	v_mov_b32_e32 v83, v0
	v_mov_b32_e32 v100, v0
	v_mov_b32_e32 v101, v0
	v_mov_b32_e32 v102, v0
	v_mov_b32_e32 v103, v0
	v_mov_b32_e32 v96, v0
	v_mov_b32_e32 v97, v0
	v_mov_b32_e32 v98, v0
	v_mov_b32_e32 v99, v0
	v_mov_b32_e32 v116, v0
	v_mov_b32_e32 v117, v0
	v_mov_b32_e32 v118, v0
	v_mov_b32_e32 v119, v0
	v_mov_b32_e32 v112, v0
	v_mov_b32_e32 v113, v0
	v_mov_b32_e32 v114, v0
	v_mov_b32_e32 v115, v0
	v_mov_b32_e32 v76, v0
	v_mov_b32_e32 v77, v0
	v_mov_b32_e32 v78, v0
	v_mov_b32_e32 v79, v0
	v_mov_b32_e32 v72, v0
	v_mov_b32_e32 v73, v0
	v_mov_b32_e32 v74, v0
	v_mov_b32_e32 v75, v0
	v_mov_b32_e32 v92, v0
	v_mov_b32_e32 v93, v0
	v_mov_b32_e32 v94, v0
	v_mov_b32_e32 v95, v0
	v_mov_b32_e32 v88, v0
	v_mov_b32_e32 v89, v0
	v_mov_b32_e32 v90, v0
	v_mov_b32_e32 v91, v0
	v_mov_b32_e32 v108, v0
	v_mov_b32_e32 v109, v0
	v_mov_b32_e32 v110, v0
	v_mov_b32_e32 v111, v0
	v_mov_b32_e32 v104, v0
	v_mov_b32_e32 v105, v0
	v_mov_b32_e32 v106, v0
	v_mov_b32_e32 v107, v0
	v_mov_b32_e32 v124, v0
	v_mov_b32_e32 v125, v0
	v_mov_b32_e32 v126, v0
	v_mov_b32_e32 v127, v0
	v_mov_b32_e32 v120, v0
	v_mov_b32_e32 v121, v0
	v_mov_b32_e32 v122, v0
	v_mov_b32_e32 v123, v0
	.p2align 6

.LBB0_697:
	v_mov_b64_e32 v[0:1], 0x800
	s_ashr_i32 s21, s20, 31
	v_cmp_lt_i64_e32 vcc, s[22:23], v[0:1]
	s_lshl_b64 s[22:23], s[20:21], 19
	s_add_u32 s22, s36, s22
	s_addc_u32 s23, s53, s23
	s_and_b64 s[24:25], vcc, exec
	s_cselect_b32 s21, s23, s27
	s_cselect_b32 s38, s22, s26
	s_ashr_i32 s7, s6, 31
	s_lshl_b64 s[24:25], s[6:7], 19
	s_add_u32 s24, s55, s24
	s_addc_u32 s25, s56, s25
	s_and_b64 s[30:31], vcc, exec
	s_cselect_b32 s7, s25, s29
	s_cselect_b32 s39, s24, s28
	s_add_u32 s26, s26, 0x40080
	s_addc_u32 s27, s27, 0
	s_add_u32 s46, s28, 0x100
	v_mov_b32_e32 v0, 0
	s_addc_u32 s50, s29, 0
	s_mov_b32 s51, -2
	v_mov_b32_e32 v1, v0
	v_mov_b32_e32 v2, v0
	v_mov_b32_e32 v3, v0
	v_mov_b32_e32 v4, v0
	v_mov_b32_e32 v5, v0
	v_mov_b32_e32 v6, v0
	v_mov_b32_e32 v7, v0
	v_mov_b32_e32 v16, v0
	v_mov_b32_e32 v17, v0
	v_mov_b32_e32 v18, v0
	v_mov_b32_e32 v19, v0
	v_mov_b32_e32 v20, v0
	v_mov_b32_e32 v21, v0
	v_mov_b32_e32 v22, v0
	v_mov_b32_e32 v23, v0
	v_mov_b32_e32 v32, v0
	v_mov_b32_e32 v33, v0
	v_mov_b32_e32 v34, v0
	v_mov_b32_e32 v35, v0
	v_mov_b32_e32 v36, v0
	v_mov_b32_e32 v37, v0
	v_mov_b32_e32 v38, v0
	v_mov_b32_e32 v39, v0
	v_mov_b32_e32 v48, v0
	v_mov_b32_e32 v49, v0
	v_mov_b32_e32 v50, v0
	v_mov_b32_e32 v51, v0
	v_mov_b32_e32 v52, v0
	v_mov_b32_e32 v53, v0
	v_mov_b32_e32 v54, v0
	v_mov_b32_e32 v55, v0
	v_mov_b32_e32 v8, v0
	v_mov_b32_e32 v9, v0
	v_mov_b32_e32 v10, v0
	v_mov_b32_e32 v11, v0
	v_mov_b32_e32 v12, v0
	v_mov_b32_e32 v13, v0
	v_mov_b32_e32 v14, v0
	v_mov_b32_e32 v15, v0
	v_mov_b32_e32 v24, v0
	v_mov_b32_e32 v25, v0
	v_mov_b32_e32 v26, v0
	v_mov_b32_e32 v27, v0
	v_mov_b32_e32 v28, v0
	v_mov_b32_e32 v29, v0
	v_mov_b32_e32 v30, v0
	v_mov_b32_e32 v31, v0
	v_mov_b32_e32 v40, v0
	v_mov_b32_e32 v41, v0
	v_mov_b32_e32 v42, v0
	v_mov_b32_e32 v43, v0
	v_mov_b32_e32 v44, v0
	v_mov_b32_e32 v45, v0
	v_mov_b32_e32 v46, v0
	v_mov_b32_e32 v47, v0
	v_mov_b32_e32 v56, v0
	v_mov_b32_e32 v57, v0
	v_mov_b32_e32 v58, v0
	v_mov_b32_e32 v59, v0
	v_mov_b32_e32 v60, v0
	v_mov_b32_e32 v61, v0
	v_mov_b32_e32 v62, v0
	v_mov_b32_e32 v63, v0
	v_mov_b32_e32 v64, v0
	v_mov_b32_e32 v65, v0
	v_mov_b32_e32 v66, v0
	v_mov_b32_e32 v67, v0
	v_mov_b32_e32 v68, v0
	v_mov_b32_e32 v69, v0
	v_mov_b32_e32 v70, v0
	v_mov_b32_e32 v71, v0
	v_mov_b32_e32 v80, v0
	v_mov_b32_e32 v81, v0
	v_mov_b32_e32 v82, v0
	v_mov_b32_e32 v83, v0
	v_mov_b32_e32 v84, v0
	v_mov_b32_e32 v85, v0
	v_mov_b32_e32 v86, v0
	v_mov_b32_e32 v87, v0
	v_mov_b32_e32 v96, v0
	v_mov_b32_e32 v97, v0
	v_mov_b32_e32 v98, v0
	v_mov_b32_e32 v99, v0
	v_mov_b32_e32 v100, v0
	v_mov_b32_e32 v101, v0
	v_mov_b32_e32 v102, v0
	v_mov_b32_e32 v103, v0
	v_mov_b32_e32 v112, v0
	v_mov_b32_e32 v113, v0
	v_mov_b32_e32 v114, v0
	v_mov_b32_e32 v115, v0
	v_mov_b32_e32 v116, v0
	v_mov_b32_e32 v117, v0
	v_mov_b32_e32 v118, v0
	v_mov_b32_e32 v119, v0
	v_mov_b32_e32 v72, v0
	v_mov_b32_e32 v73, v0
	v_mov_b32_e32 v74, v0
	v_mov_b32_e32 v75, v0
	v_mov_b32_e32 v76, v0
	v_mov_b32_e32 v77, v0
	v_mov_b32_e32 v78, v0
	v_mov_b32_e32 v79, v0
	v_mov_b32_e32 v88, v0
	v_mov_b32_e32 v89, v0
	v_mov_b32_e32 v90, v0
	v_mov_b32_e32 v91, v0
	v_mov_b32_e32 v92, v0
	v_mov_b32_e32 v93, v0
	v_mov_b32_e32 v94, v0
	v_mov_b32_e32 v95, v0
	v_mov_b32_e32 v104, v0
	v_mov_b32_e32 v105, v0
	v_mov_b32_e32 v106, v0
	v_mov_b32_e32 v107, v0
	v_mov_b32_e32 v108, v0
	v_mov_b32_e32 v109, v0
	v_mov_b32_e32 v110, v0
	v_mov_b32_e32 v111, v0
	v_mov_b32_e32 v120, v0
	v_mov_b32_e32 v121, v0
	v_mov_b32_e32 v122, v0
	v_mov_b32_e32 v123, v0
	v_mov_b32_e32 v124, v0
	v_mov_b32_e32 v125, v0
	v_mov_b32_e32 v126, v0
	v_mov_b32_e32 v127, v0
	.p2align 6

.LBB0_713:
	s_ashr_i32 s21, s20, 31
	v_cmp_lt_i64_e32 vcc, s[22:23], v[222:223]
	s_lshl_b64 s[22:23], s[20:21], 19
	s_add_u32 s22, s31, s22
	s_addc_u32 s23, s54, s23
	s_and_b64 s[24:25], vcc, exec
	s_cselect_b32 s21, s23, s7
	s_cselect_b32 s38, s22, s6
	s_ashr_i32 s11, s10, 31
	s_lshl_b64 s[24:25], s[10:11], 19
	s_add_u32 s24, s36, s24
	s_addc_u32 s25, s53, s25
	s_and_b64 s[28:29], vcc, exec
	s_cselect_b32 s11, s25, s27
	s_cselect_b32 s39, s24, s26
	s_add_u32 s6, s6, 0x40080
	s_addc_u32 s7, s7, 0
	s_add_u32 s46, s26, 0x100
	v_mov_b32_e32 v0, 0
	s_addc_u32 s50, s27, 0
	s_mov_b32 s51, -2
	v_mov_b32_e32 v1, v0
	v_mov_b32_e32 v2, v0
	v_mov_b32_e32 v3, v0
	v_mov_b32_e32 v4, v0
	v_mov_b32_e32 v5, v0
	v_mov_b32_e32 v6, v0
	v_mov_b32_e32 v7, v0
	v_mov_b32_e32 v8, v0
	v_mov_b32_e32 v9, v0
	v_mov_b32_e32 v10, v0
	v_mov_b32_e32 v11, v0
	v_mov_b32_e32 v12, v0
	v_mov_b32_e32 v13, v0
	v_mov_b32_e32 v14, v0
	v_mov_b32_e32 v15, v0
	v_mov_b32_e32 v16, v0
	v_mov_b32_e32 v17, v0
	v_mov_b32_e32 v18, v0
	v_mov_b32_e32 v19, v0
	v_mov_b32_e32 v20, v0
	v_mov_b32_e32 v21, v0
	v_mov_b32_e32 v22, v0
	v_mov_b32_e32 v23, v0
	v_mov_b32_e32 v24, v0
	v_mov_b32_e32 v25, v0
	v_mov_b32_e32 v26, v0
	v_mov_b32_e32 v27, v0
	v_mov_b32_e32 v28, v0
	v_mov_b32_e32 v29, v0
	v_mov_b32_e32 v30, v0
	v_mov_b32_e32 v31, v0
	v_mov_b32_e32 v64, v0
	v_mov_b32_e32 v65, v0
	v_mov_b32_e32 v66, v0
	v_mov_b32_e32 v67, v0
	v_mov_b32_e32 v68, v0
	v_mov_b32_e32 v69, v0
	v_mov_b32_e32 v70, v0
	v_mov_b32_e32 v71, v0
	v_mov_b32_e32 v72, v0
	v_mov_b32_e32 v73, v0
	v_mov_b32_e32 v74, v0
	v_mov_b32_e32 v75, v0
	v_mov_b32_e32 v76, v0
	v_mov_b32_e32 v77, v0
	v_mov_b32_e32 v78, v0
	v_mov_b32_e32 v79, v0
	v_mov_b32_e32 v80, v0
	v_mov_b32_e32 v81, v0
	v_mov_b32_e32 v82, v0
	v_mov_b32_e32 v83, v0
	v_mov_b32_e32 v84, v0
	v_mov_b32_e32 v85, v0
	v_mov_b32_e32 v86, v0
	v_mov_b32_e32 v87, v0
	v_mov_b32_e32 v88, v0
	v_mov_b32_e32 v89, v0
	v_mov_b32_e32 v90, v0
	v_mov_b32_e32 v91, v0
	v_mov_b32_e32 v92, v0
	v_mov_b32_e32 v93, v0
	v_mov_b32_e32 v94, v0
	v_mov_b32_e32 v95, v0
	v_mov_b32_e32 v32, v0
	v_mov_b32_e32 v33, v0
	v_mov_b32_e32 v34, v0
	v_mov_b32_e32 v35, v0
	v_mov_b32_e32 v36, v0
	v_mov_b32_e32 v37, v0
	v_mov_b32_e32 v38, v0
	v_mov_b32_e32 v39, v0
	v_mov_b32_e32 v40, v0
	v_mov_b32_e32 v41, v0
	v_mov_b32_e32 v42, v0
	v_mov_b32_e32 v43, v0
	v_mov_b32_e32 v44, v0
	v_mov_b32_e32 v45, v0
	v_mov_b32_e32 v46, v0
	v_mov_b32_e32 v47, v0
	v_mov_b32_e32 v48, v0
	v_mov_b32_e32 v49, v0
	v_mov_b32_e32 v50, v0
	v_mov_b32_e32 v51, v0
	v_mov_b32_e32 v52, v0
	v_mov_b32_e32 v53, v0
	v_mov_b32_e32 v54, v0
	v_mov_b32_e32 v55, v0
	v_mov_b32_e32 v56, v0
	v_mov_b32_e32 v57, v0
	v_mov_b32_e32 v58, v0
	v_mov_b32_e32 v59, v0
	v_mov_b32_e32 v60, v0
	v_mov_b32_e32 v61, v0
	v_mov_b32_e32 v62, v0
	v_mov_b32_e32 v63, v0
	v_mov_b32_e32 v96, v0
	v_mov_b32_e32 v97, v0
	v_mov_b32_e32 v98, v0
	v_mov_b32_e32 v99, v0
	v_mov_b32_e32 v100, v0
	v_mov_b32_e32 v101, v0
	v_mov_b32_e32 v102, v0
	v_mov_b32_e32 v103, v0
	v_mov_b32_e32 v104, v0
	v_mov_b32_e32 v105, v0
	v_mov_b32_e32 v106, v0
	v_mov_b32_e32 v107, v0
	v_mov_b32_e32 v108, v0
	v_mov_b32_e32 v109, v0
	v_mov_b32_e32 v110, v0
	v_mov_b32_e32 v111, v0
	v_mov_b32_e32 v112, v0
	v_mov_b32_e32 v113, v0
	v_mov_b32_e32 v114, v0
	v_mov_b32_e32 v115, v0
	v_mov_b32_e32 v116, v0
	v_mov_b32_e32 v117, v0
	v_mov_b32_e32 v118, v0
	v_mov_b32_e32 v119, v0
	v_mov_b32_e32 v120, v0
	v_mov_b32_e32 v121, v0
	v_mov_b32_e32 v122, v0
	v_mov_b32_e32 v123, v0
	v_mov_b32_e32 v124, v0
	v_mov_b32_e32 v125, v0
	v_mov_b32_e32 v126, v0
	v_mov_b32_e32 v127, v0
	.p2align 6

.LBB0_775:
	s_ashr_i32 s21, s20, 31
	v_cmp_lt_i64_e32 vcc, s[22:23], v[222:223]
	s_lshl_b64 s[22:23], s[20:21], 19
	s_add_u32 s22, s35, s22
	s_addc_u32 s23, s46, s23
	s_and_b64 s[24:25], vcc, exec
	s_cselect_b32 s21, s23, s27
	s_cselect_b32 s39, s22, s26
	s_ashr_i32 s19, s18, 31
	s_lshl_b64 s[24:25], s[18:19], 19
	s_add_u32 s24, s50, s24
	s_addc_u32 s25, s51, s25
	s_and_b64 s[30:31], vcc, exec
	s_cselect_b32 s19, s25, s29
	s_cselect_b32 s62, s24, s28
	s_add_u32 s26, s26, 0x40080
	s_addc_u32 s27, s27, 0
	s_add_u32 s63, s28, 0x100
	v_mov_b32_e32 v0, 0
	s_addc_u32 s64, s29, 0
	s_mov_b32 s65, -2
	s_waitcnt lgkmcnt(0)
	v_mov_b32_e32 v1, v0
	v_mov_b32_e32 v2, v0
	v_mov_b32_e32 v3, v0
	v_mov_b32_e32 v4, v0
	v_mov_b32_e32 v5, v0
	v_mov_b32_e32 v6, v0
	v_mov_b32_e32 v7, v0
	v_mov_b32_e32 v16, v0
	v_mov_b32_e32 v17, v0
	v_mov_b32_e32 v18, v0
	v_mov_b32_e32 v19, v0
	v_mov_b32_e32 v20, v0
	v_mov_b32_e32 v21, v0
	v_mov_b32_e32 v22, v0
	v_mov_b32_e32 v23, v0
	v_mov_b32_e32 v32, v0
	v_mov_b32_e32 v33, v0
	v_mov_b32_e32 v34, v0
	v_mov_b32_e32 v35, v0
	v_mov_b32_e32 v36, v0
	v_mov_b32_e32 v37, v0
	v_mov_b32_e32 v38, v0
	v_mov_b32_e32 v39, v0
	v_mov_b32_e32 v48, v0
	v_mov_b32_e32 v49, v0
	v_mov_b32_e32 v50, v0
	v_mov_b32_e32 v51, v0
	v_mov_b32_e32 v52, v0
	v_mov_b32_e32 v53, v0
	v_mov_b32_e32 v54, v0
	v_mov_b32_e32 v55, v0
	v_mov_b32_e32 v8, v0
	v_mov_b32_e32 v9, v0
	v_mov_b32_e32 v10, v0
	v_mov_b32_e32 v11, v0
	v_mov_b32_e32 v12, v0
	v_mov_b32_e32 v13, v0
	v_mov_b32_e32 v14, v0
	v_mov_b32_e32 v15, v0
	v_mov_b32_e32 v24, v0
	v_mov_b32_e32 v25, v0
	v_mov_b32_e32 v26, v0
	v_mov_b32_e32 v27, v0
	v_mov_b32_e32 v28, v0
	v_mov_b32_e32 v29, v0
	v_mov_b32_e32 v30, v0
	v_mov_b32_e32 v31, v0
	v_mov_b32_e32 v40, v0
	v_mov_b32_e32 v41, v0
	v_mov_b32_e32 v42, v0
	v_mov_b32_e32 v43, v0
	v_mov_b32_e32 v44, v0
	v_mov_b32_e32 v45, v0
	v_mov_b32_e32 v46, v0
	v_mov_b32_e32 v47, v0
	v_mov_b32_e32 v56, v0
	v_mov_b32_e32 v57, v0
	v_mov_b32_e32 v58, v0
	v_mov_b32_e32 v59, v0
	v_mov_b32_e32 v60, v0
	v_mov_b32_e32 v61, v0
	v_mov_b32_e32 v62, v0
	v_mov_b32_e32 v63, v0
	v_mov_b32_e32 v64, v0
	v_mov_b32_e32 v65, v0
	v_mov_b32_e32 v66, v0
	v_mov_b32_e32 v67, v0
	v_mov_b32_e32 v68, v0
	v_mov_b32_e32 v69, v0
	v_mov_b32_e32 v70, v0
	v_mov_b32_e32 v71, v0
	v_mov_b32_e32 v80, v0
	v_mov_b32_e32 v81, v0
	v_mov_b32_e32 v82, v0
	v_mov_b32_e32 v83, v0
	v_mov_b32_e32 v84, v0
	v_mov_b32_e32 v85, v0
	v_mov_b32_e32 v86, v0
	v_mov_b32_e32 v87, v0
	v_mov_b32_e32 v96, v0
	v_mov_b32_e32 v97, v0
	v_mov_b32_e32 v98, v0
	v_mov_b32_e32 v99, v0
	v_mov_b32_e32 v100, v0
	v_mov_b32_e32 v101, v0
	v_mov_b32_e32 v102, v0
	v_mov_b32_e32 v103, v0
	v_mov_b32_e32 v112, v0
	v_mov_b32_e32 v113, v0
	v_mov_b32_e32 v114, v0
	v_mov_b32_e32 v115, v0
	v_mov_b32_e32 v116, v0
	v_mov_b32_e32 v117, v0
	v_mov_b32_e32 v118, v0
	v_mov_b32_e32 v119, v0
	v_mov_b32_e32 v72, v0
	v_mov_b32_e32 v73, v0
	v_mov_b32_e32 v74, v0
	v_mov_b32_e32 v75, v0
	v_mov_b32_e32 v76, v0
	v_mov_b32_e32 v77, v0
	v_mov_b32_e32 v78, v0
	v_mov_b32_e32 v79, v0
	v_mov_b32_e32 v88, v0
	v_mov_b32_e32 v89, v0
	v_mov_b32_e32 v90, v0
	v_mov_b32_e32 v91, v0
	v_mov_b32_e32 v92, v0
	v_mov_b32_e32 v93, v0
	v_mov_b32_e32 v94, v0
	v_mov_b32_e32 v95, v0
	v_mov_b32_e32 v104, v0
	v_mov_b32_e32 v105, v0
	v_mov_b32_e32 v106, v0
	v_mov_b32_e32 v107, v0
	v_mov_b32_e32 v108, v0
	v_mov_b32_e32 v109, v0
	v_mov_b32_e32 v110, v0
	v_mov_b32_e32 v111, v0
	v_mov_b32_e32 v120, v0
	v_mov_b32_e32 v121, v0
	v_mov_b32_e32 v122, v0
	v_mov_b32_e32 v123, v0
	v_mov_b32_e32 v124, v0
	v_mov_b32_e32 v125, v0
	v_mov_b32_e32 v126, v0
	v_mov_b32_e32 v127, v0
	.p2align 6

.LBB0_822:
	s_ashr_i32 s19, s18, 31
	v_cmp_lt_i64_e32 vcc, s[20:21], v[222:223]
	s_lshl_b64 s[20:21], s[18:19], 19
	s_add_u32 s20, s31, s20
	s_addc_u32 s21, s36, s21
	s_and_b64 s[22:23], vcc, exec
	s_cselect_b32 s19, s21, s25
	s_cselect_b32 s38, s20, s24
	s_ashr_i32 s17, s16, 31
	s_lshl_b64 s[22:23], s[16:17], 19
	s_add_u32 s22, s47, s22
	s_addc_u32 s23, s56, s23
	s_and_b64 s[28:29], vcc, exec
	s_cselect_b32 s17, s23, s27
	s_cselect_b32 s39, s22, s26
	s_add_u32 s24, s24, 0x40080
	s_addc_u32 s25, s25, 0
	s_add_u32 s46, s26, 0x100
	v_mov_b32_e32 v0, 0
	s_addc_u32 s50, s27, 0
	s_mov_b32 s51, -2
	v_mov_b32_e32 v1, v0
	v_mov_b32_e32 v2, v0
	v_mov_b32_e32 v3, v0
	v_mov_b32_e32 v4, v0
	v_mov_b32_e32 v5, v0
	v_mov_b32_e32 v6, v0
	v_mov_b32_e32 v7, v0
	v_mov_b32_e32 v16, v0
	v_mov_b32_e32 v17, v0
	v_mov_b32_e32 v18, v0
	v_mov_b32_e32 v19, v0
	v_mov_b32_e32 v20, v0
	v_mov_b32_e32 v21, v0
	v_mov_b32_e32 v22, v0
	v_mov_b32_e32 v23, v0
	v_mov_b32_e32 v32, v0
	v_mov_b32_e32 v33, v0
	v_mov_b32_e32 v34, v0
	v_mov_b32_e32 v35, v0
	v_mov_b32_e32 v36, v0
	v_mov_b32_e32 v37, v0
	v_mov_b32_e32 v38, v0
	v_mov_b32_e32 v39, v0
	v_mov_b32_e32 v48, v0
	v_mov_b32_e32 v49, v0
	v_mov_b32_e32 v50, v0
	v_mov_b32_e32 v51, v0
	v_mov_b32_e32 v52, v0
	v_mov_b32_e32 v53, v0
	v_mov_b32_e32 v54, v0
	v_mov_b32_e32 v55, v0
	v_mov_b32_e32 v8, v0
	v_mov_b32_e32 v9, v0
	v_mov_b32_e32 v10, v0
	v_mov_b32_e32 v11, v0
	v_mov_b32_e32 v12, v0
	v_mov_b32_e32 v13, v0
	v_mov_b32_e32 v14, v0
	v_mov_b32_e32 v15, v0
	v_mov_b32_e32 v24, v0
	v_mov_b32_e32 v25, v0
	v_mov_b32_e32 v26, v0
	v_mov_b32_e32 v27, v0
	v_mov_b32_e32 v28, v0
	v_mov_b32_e32 v29, v0
	v_mov_b32_e32 v30, v0
	v_mov_b32_e32 v31, v0
	v_mov_b32_e32 v40, v0
	v_mov_b32_e32 v41, v0
	v_mov_b32_e32 v42, v0
	v_mov_b32_e32 v43, v0
	v_mov_b32_e32 v44, v0
	v_mov_b32_e32 v45, v0
	v_mov_b32_e32 v46, v0
	v_mov_b32_e32 v47, v0
	v_mov_b32_e32 v56, v0
	v_mov_b32_e32 v57, v0
	v_mov_b32_e32 v58, v0
	v_mov_b32_e32 v59, v0
	v_mov_b32_e32 v60, v0
	v_mov_b32_e32 v61, v0
	v_mov_b32_e32 v62, v0
	v_mov_b32_e32 v63, v0
	v_mov_b32_e32 v64, v0
	v_mov_b32_e32 v65, v0
	v_mov_b32_e32 v66, v0
	v_mov_b32_e32 v67, v0
	v_mov_b32_e32 v68, v0
	v_mov_b32_e32 v69, v0
	v_mov_b32_e32 v70, v0
	v_mov_b32_e32 v71, v0
	v_mov_b32_e32 v80, v0
	v_mov_b32_e32 v81, v0
	v_mov_b32_e32 v82, v0
	v_mov_b32_e32 v83, v0
	v_mov_b32_e32 v84, v0
	v_mov_b32_e32 v85, v0
	v_mov_b32_e32 v86, v0
	v_mov_b32_e32 v87, v0
	v_mov_b32_e32 v96, v0
	v_mov_b32_e32 v97, v0
	v_mov_b32_e32 v98, v0
	v_mov_b32_e32 v99, v0
	v_mov_b32_e32 v100, v0
	v_mov_b32_e32 v101, v0
	v_mov_b32_e32 v102, v0
	v_mov_b32_e32 v103, v0
	v_mov_b32_e32 v112, v0
	v_mov_b32_e32 v113, v0
	v_mov_b32_e32 v114, v0
	v_mov_b32_e32 v115, v0
	v_mov_b32_e32 v116, v0
	v_mov_b32_e32 v117, v0
	v_mov_b32_e32 v118, v0
	v_mov_b32_e32 v119, v0
	v_mov_b32_e32 v72, v0
	v_mov_b32_e32 v73, v0
	v_mov_b32_e32 v74, v0
	v_mov_b32_e32 v75, v0
	v_mov_b32_e32 v76, v0
	v_mov_b32_e32 v77, v0
	v_mov_b32_e32 v78, v0
	v_mov_b32_e32 v79, v0
	v_mov_b32_e32 v88, v0
	v_mov_b32_e32 v89, v0
	v_mov_b32_e32 v90, v0
	v_mov_b32_e32 v91, v0
	v_mov_b32_e32 v92, v0
	v_mov_b32_e32 v93, v0
	v_mov_b32_e32 v94, v0
	v_mov_b32_e32 v95, v0
	v_mov_b32_e32 v104, v0
	v_mov_b32_e32 v105, v0
	v_mov_b32_e32 v106, v0
	v_mov_b32_e32 v107, v0
	v_mov_b32_e32 v108, v0
	v_mov_b32_e32 v109, v0
	v_mov_b32_e32 v110, v0
	v_mov_b32_e32 v111, v0
	v_mov_b32_e32 v120, v0
	v_mov_b32_e32 v121, v0
	v_mov_b32_e32 v122, v0
	v_mov_b32_e32 v123, v0
	v_mov_b32_e32 v124, v0
	v_mov_b32_e32 v125, v0
	v_mov_b32_e32 v126, v0
	v_mov_b32_e32 v127, v0
	.p2align 6

.LBB0_877:
	s_ashr_i32 s19, s18, 31
	v_cmp_lt_i64_e32 vcc, s[20:21], v[222:223]
	s_lshl_b64 s[20:21], s[18:19], 19
	s_add_u32 s20, s31, s20
	s_addc_u32 s21, s34, s21
	s_and_b64 s[22:23], vcc, exec
	s_cselect_b32 s19, s21, s25
	s_cselect_b32 s39, s20, s24
	s_ashr_i32 s17, s16, 31
	s_lshl_b64 s[22:23], s[16:17], 19
	s_add_u32 s22, s35, s22
	s_addc_u32 s23, s46, s23
	s_and_b64 s[28:29], vcc, exec
	s_cselect_b32 s17, s23, s27
	s_cselect_b32 s61, s22, s26
	s_add_u32 s24, s24, 0x40080
	s_addc_u32 s25, s25, 0
	s_add_u32 s62, s26, 0x100
	v_mov_b32_e32 v0, 0
	s_addc_u32 s63, s27, 0
	s_mov_b32 s64, -2
	s_waitcnt lgkmcnt(0)
	v_mov_b32_e32 v1, v0
	v_mov_b32_e32 v2, v0
	v_mov_b32_e32 v3, v0
	v_mov_b32_e32 v4, v0
	v_mov_b32_e32 v5, v0
	v_mov_b32_e32 v6, v0
	v_mov_b32_e32 v7, v0
	v_mov_b32_e32 v16, v0
	v_mov_b32_e32 v17, v0
	v_mov_b32_e32 v18, v0
	v_mov_b32_e32 v19, v0
	v_mov_b32_e32 v20, v0
	v_mov_b32_e32 v21, v0
	v_mov_b32_e32 v22, v0
	v_mov_b32_e32 v23, v0
	v_mov_b32_e32 v32, v0
	v_mov_b32_e32 v33, v0
	v_mov_b32_e32 v34, v0
	v_mov_b32_e32 v35, v0
	v_mov_b32_e32 v36, v0
	v_mov_b32_e32 v37, v0
	v_mov_b32_e32 v38, v0
	v_mov_b32_e32 v39, v0
	v_mov_b32_e32 v48, v0
	v_mov_b32_e32 v49, v0
	v_mov_b32_e32 v50, v0
	v_mov_b32_e32 v51, v0
	v_mov_b32_e32 v52, v0
	v_mov_b32_e32 v53, v0
	v_mov_b32_e32 v54, v0
	v_mov_b32_e32 v55, v0
	v_mov_b32_e32 v8, v0
	v_mov_b32_e32 v9, v0
	v_mov_b32_e32 v10, v0
	v_mov_b32_e32 v11, v0
	v_mov_b32_e32 v12, v0
	v_mov_b32_e32 v13, v0
	v_mov_b32_e32 v14, v0
	v_mov_b32_e32 v15, v0
	v_mov_b32_e32 v24, v0
	v_mov_b32_e32 v25, v0
	v_mov_b32_e32 v26, v0
	v_mov_b32_e32 v27, v0
	v_mov_b32_e32 v28, v0
	v_mov_b32_e32 v29, v0
	v_mov_b32_e32 v30, v0
	v_mov_b32_e32 v31, v0
	v_mov_b32_e32 v40, v0
	v_mov_b32_e32 v41, v0
	v_mov_b32_e32 v42, v0
	v_mov_b32_e32 v43, v0
	v_mov_b32_e32 v44, v0
	v_mov_b32_e32 v45, v0
	v_mov_b32_e32 v46, v0
	v_mov_b32_e32 v47, v0
	v_mov_b32_e32 v56, v0
	v_mov_b32_e32 v57, v0
	v_mov_b32_e32 v58, v0
	v_mov_b32_e32 v59, v0
	v_mov_b32_e32 v60, v0
	v_mov_b32_e32 v61, v0
	v_mov_b32_e32 v62, v0
	v_mov_b32_e32 v63, v0
	v_mov_b32_e32 v64, v0
	v_mov_b32_e32 v65, v0
	v_mov_b32_e32 v66, v0
	v_mov_b32_e32 v67, v0
	v_mov_b32_e32 v68, v0
	v_mov_b32_e32 v69, v0
	v_mov_b32_e32 v70, v0
	v_mov_b32_e32 v71, v0
	v_mov_b32_e32 v80, v0
	v_mov_b32_e32 v81, v0
	v_mov_b32_e32 v82, v0
	v_mov_b32_e32 v83, v0
	v_mov_b32_e32 v84, v0
	v_mov_b32_e32 v85, v0
	v_mov_b32_e32 v86, v0
	v_mov_b32_e32 v87, v0
	v_mov_b32_e32 v96, v0
	v_mov_b32_e32 v97, v0
	v_mov_b32_e32 v98, v0
	v_mov_b32_e32 v99, v0
	v_mov_b32_e32 v100, v0
	v_mov_b32_e32 v101, v0
	v_mov_b32_e32 v102, v0
	v_mov_b32_e32 v103, v0
	v_mov_b32_e32 v112, v0
	v_mov_b32_e32 v113, v0
	v_mov_b32_e32 v114, v0
	v_mov_b32_e32 v115, v0
	v_mov_b32_e32 v116, v0
	v_mov_b32_e32 v117, v0
	v_mov_b32_e32 v118, v0
	v_mov_b32_e32 v119, v0
	v_mov_b32_e32 v72, v0
	v_mov_b32_e32 v73, v0
	v_mov_b32_e32 v74, v0
	v_mov_b32_e32 v75, v0
	v_mov_b32_e32 v76, v0
	v_mov_b32_e32 v77, v0
	v_mov_b32_e32 v78, v0
	v_mov_b32_e32 v79, v0
	v_mov_b32_e32 v88, v0
	v_mov_b32_e32 v89, v0
	v_mov_b32_e32 v90, v0
	v_mov_b32_e32 v91, v0
	v_mov_b32_e32 v92, v0
	v_mov_b32_e32 v93, v0
	v_mov_b32_e32 v94, v0
	v_mov_b32_e32 v95, v0
	v_mov_b32_e32 v104, v0
	v_mov_b32_e32 v105, v0
	v_mov_b32_e32 v106, v0
	v_mov_b32_e32 v107, v0
	v_mov_b32_e32 v108, v0
	v_mov_b32_e32 v109, v0
	v_mov_b32_e32 v110, v0
	v_mov_b32_e32 v111, v0
	v_mov_b32_e32 v120, v0
	v_mov_b32_e32 v121, v0
	v_mov_b32_e32 v122, v0
	v_mov_b32_e32 v123, v0
	v_mov_b32_e32 v124, v0
	v_mov_b32_e32 v125, v0
	v_mov_b32_e32 v126, v0
	v_mov_b32_e32 v127, v0
	.p2align 6

.LBB0_920:
	v_mov_b64_e32 v[0:1], 0x1600
	s_ashr_i32 s67, s66, 31
	v_cmp_lt_i64_e32 vcc, s[6:7], v[0:1]
	s_lshl_b64 s[6:7], s[66:67], 19
	s_add_u32 s68, s76, s6
	s_addc_u32 s69, s77, s7
	s_and_b64 s[6:7], vcc, exec
	s_cselect_b32 s15, s69, s11
	s_cselect_b32 s39, s68, s10
	s_ashr_i32 s65, s64, 31
	s_lshl_b64 s[6:7], s[64:65], 19
	s_add_u32 s70, s82, s6
	s_addc_u32 s71, s75, s7
	s_and_b64 s[6:7], vcc, exec
	s_cselect_b32 s65, s71, s9
	s_cselect_b32 s67, s70, s8
	s_add_u32 s6, s10, 0x20080
	s_addc_u32 s7, s11, 0
	s_add_u32 vcc_lo, s8, 0x100
	v_mov_b32_e32 v96, 0
	s_addc_u32 vcc_hi, s9, 0
	s_mov_b32 s73, -2
	v_mov_b32_e32 v97, v96
	v_mov_b32_e32 v98, v96
	v_mov_b32_e32 v99, v96
	v_mov_b32_e32 v100, v96
	v_mov_b32_e32 v101, v96
	v_mov_b32_e32 v102, v96
	v_mov_b32_e32 v103, v96
	v_mov_b32_e32 v0, v96
	v_mov_b32_e32 v1, v96
	v_mov_b32_e32 v2, v96
	v_mov_b32_e32 v3, v96
	v_mov_b32_e32 v48, v96
	v_mov_b32_e32 v49, v96
	v_mov_b32_e32 v50, v96
	v_mov_b32_e32 v51, v96
	v_mov_b32_e32 v4, v96
	v_mov_b32_e32 v5, v96
	v_mov_b32_e32 v6, v96
	v_mov_b32_e32 v7, v96
	v_mov_b32_e32 v52, v96
	v_mov_b32_e32 v53, v96
	v_mov_b32_e32 v54, v96
	v_mov_b32_e32 v55, v96
	v_mov_b32_e32 v8, v96
	v_mov_b32_e32 v9, v96
	v_mov_b32_e32 v10, v96
	v_mov_b32_e32 v11, v96
	v_mov_b32_e32 v56, v96
	v_mov_b32_e32 v57, v96
	v_mov_b32_e32 v58, v96
	v_mov_b32_e32 v59, v96
	v_mov_b32_e32 v104, v96
	v_mov_b32_e32 v105, v96
	v_mov_b32_e32 v106, v96
	v_mov_b32_e32 v107, v96
	v_mov_b32_e32 v108, v96
	v_mov_b32_e32 v109, v96
	v_mov_b32_e32 v110, v96
	v_mov_b32_e32 v111, v96
	v_mov_b32_e32 v12, v96
	v_mov_b32_e32 v13, v96
	v_mov_b32_e32 v14, v96
	v_mov_b32_e32 v15, v96
	v_mov_b32_e32 v60, v96
	v_mov_b32_e32 v61, v96
	v_mov_b32_e32 v62, v96
	v_mov_b32_e32 v63, v96
	v_mov_b32_e32 v16, v96
	v_mov_b32_e32 v17, v96
	v_mov_b32_e32 v18, v96
	v_mov_b32_e32 v19, v96
	v_mov_b32_e32 v64, v96
	v_mov_b32_e32 v65, v96
	v_mov_b32_e32 v66, v96
	v_mov_b32_e32 v67, v96
	v_mov_b32_e32 v20, v96
	v_mov_b32_e32 v21, v96
	v_mov_b32_e32 v22, v96
	v_mov_b32_e32 v23, v96
	v_mov_b32_e32 v68, v96
	v_mov_b32_e32 v69, v96
	v_mov_b32_e32 v70, v96
	v_mov_b32_e32 v71, v96
	v_mov_b32_e32 v24, v96
	v_mov_b32_e32 v25, v96
	v_mov_b32_e32 v26, v96
	v_mov_b32_e32 v27, v96
	v_mov_b32_e32 v72, v96
	v_mov_b32_e32 v73, v96
	v_mov_b32_e32 v74, v96
	v_mov_b32_e32 v75, v96
	v_mov_b32_e32 v28, v96
	v_mov_b32_e32 v29, v96
	v_mov_b32_e32 v30, v96
	v_mov_b32_e32 v31, v96
	v_mov_b32_e32 v80, v96
	v_mov_b32_e32 v81, v96
	v_mov_b32_e32 v82, v96
	v_mov_b32_e32 v83, v96
	v_mov_b32_e32 v32, v96
	v_mov_b32_e32 v33, v96
	v_mov_b32_e32 v34, v96
	v_mov_b32_e32 v35, v96
	v_mov_b32_e32 v88, v96
	v_mov_b32_e32 v89, v96
	v_mov_b32_e32 v90, v96
	v_mov_b32_e32 v91, v96
	v_mov_b32_e32 v112, v96
	v_mov_b32_e32 v113, v96
	v_mov_b32_e32 v114, v96
	v_mov_b32_e32 v115, v96
	v_mov_b32_e32 v116, v96
	v_mov_b32_e32 v117, v96
	v_mov_b32_e32 v118, v96
	v_mov_b32_e32 v119, v96
	v_mov_b32_e32 v36, v96
	v_mov_b32_e32 v37, v96
	v_mov_b32_e32 v38, v96
	v_mov_b32_e32 v39, v96
	v_mov_b32_e32 v76, v96
	v_mov_b32_e32 v77, v96
	v_mov_b32_e32 v78, v96
	v_mov_b32_e32 v79, v96
	v_mov_b32_e32 v40, v96
	v_mov_b32_e32 v41, v96
	v_mov_b32_e32 v42, v96
	v_mov_b32_e32 v43, v96
	v_mov_b32_e32 v84, v96
	v_mov_b32_e32 v85, v96
	v_mov_b32_e32 v86, v96
	v_mov_b32_e32 v87, v96
	v_mov_b32_e32 v44, v96
	v_mov_b32_e32 v45, v96
	v_mov_b32_e32 v46, v96
	v_mov_b32_e32 v47, v96
	v_mov_b32_e32 v92, v96
	v_mov_b32_e32 v93, v96
	v_mov_b32_e32 v94, v96
	v_mov_b32_e32 v95, v96
	v_mov_b32_e32 v120, v96
	v_mov_b32_e32 v121, v96
	v_mov_b32_e32 v122, v96
	v_mov_b32_e32 v123, v96
	v_mov_b32_e32 v124, v96
	v_mov_b32_e32 v125, v96
	v_mov_b32_e32 v126, v96
	v_mov_b32_e32 v127, v96
	.p2align 6

.LBB0_997:
	s_add_u32 s57, s20, 0x100
	v_mov_b32_e32 v0, 0
	s_addc_u32 s58, s21, 0
	s_mov_b32 s59, -2
	v_mov_b32_e32 v1, v0
	v_mov_b32_e32 v2, v0
	v_mov_b32_e32 v3, v0
	v_mov_b32_e32 v4, v0
	v_mov_b32_e32 v5, v0
	v_mov_b32_e32 v6, v0
	v_mov_b32_e32 v7, v0
	v_mov_b32_e32 v16, v0
	v_mov_b32_e32 v17, v0
	v_mov_b32_e32 v18, v0
	v_mov_b32_e32 v19, v0
	v_mov_b32_e32 v20, v0
	v_mov_b32_e32 v21, v0
	v_mov_b32_e32 v22, v0
	v_mov_b32_e32 v23, v0
	v_mov_b32_e32 v32, v0
	v_mov_b32_e32 v33, v0
	v_mov_b32_e32 v34, v0
	v_mov_b32_e32 v35, v0
	v_mov_b32_e32 v36, v0
	v_mov_b32_e32 v37, v0
	v_mov_b32_e32 v38, v0
	v_mov_b32_e32 v39, v0
	v_mov_b32_e32 v48, v0
	v_mov_b32_e32 v49, v0
	v_mov_b32_e32 v50, v0
	v_mov_b32_e32 v51, v0
	v_mov_b32_e32 v52, v0
	v_mov_b32_e32 v53, v0
	v_mov_b32_e32 v54, v0
	v_mov_b32_e32 v55, v0
	v_mov_b32_e32 v8, v0
	v_mov_b32_e32 v9, v0
	v_mov_b32_e32 v10, v0
	v_mov_b32_e32 v11, v0
	v_mov_b32_e32 v12, v0
	v_mov_b32_e32 v13, v0
	v_mov_b32_e32 v14, v0
	v_mov_b32_e32 v15, v0
	v_mov_b32_e32 v24, v0
	v_mov_b32_e32 v25, v0
	v_mov_b32_e32 v26, v0
	v_mov_b32_e32 v27, v0
	v_mov_b32_e32 v28, v0
	v_mov_b32_e32 v29, v0
	v_mov_b32_e32 v30, v0
	v_mov_b32_e32 v31, v0
	v_mov_b32_e32 v40, v0
	v_mov_b32_e32 v41, v0
	v_mov_b32_e32 v42, v0
	v_mov_b32_e32 v43, v0
	v_mov_b32_e32 v44, v0
	v_mov_b32_e32 v45, v0
	v_mov_b32_e32 v46, v0
	v_mov_b32_e32 v47, v0
	v_mov_b32_e32 v56, v0
	v_mov_b32_e32 v57, v0
	v_mov_b32_e32 v58, v0
	v_mov_b32_e32 v59, v0
	v_mov_b32_e32 v60, v0
	v_mov_b32_e32 v61, v0
	v_mov_b32_e32 v62, v0
	v_mov_b32_e32 v63, v0
	v_mov_b32_e32 v64, v0
	v_mov_b32_e32 v65, v0
	v_mov_b32_e32 v66, v0
	v_mov_b32_e32 v67, v0
	v_mov_b32_e32 v68, v0
	v_mov_b32_e32 v69, v0
	v_mov_b32_e32 v70, v0
	v_mov_b32_e32 v71, v0
	v_mov_b32_e32 v80, v0
	v_mov_b32_e32 v81, v0
	v_mov_b32_e32 v82, v0
	v_mov_b32_e32 v83, v0
	v_mov_b32_e32 v84, v0
	v_mov_b32_e32 v85, v0
	v_mov_b32_e32 v86, v0
	v_mov_b32_e32 v87, v0
	v_mov_b32_e32 v96, v0
	v_mov_b32_e32 v97, v0
	v_mov_b32_e32 v98, v0
	v_mov_b32_e32 v99, v0
	v_mov_b32_e32 v100, v0
	v_mov_b32_e32 v101, v0
	v_mov_b32_e32 v102, v0
	v_mov_b32_e32 v103, v0
	v_mov_b32_e32 v112, v0
	v_mov_b32_e32 v113, v0
	v_mov_b32_e32 v114, v0
	v_mov_b32_e32 v115, v0
	v_mov_b32_e32 v116, v0
	v_mov_b32_e32 v117, v0
	v_mov_b32_e32 v118, v0
	v_mov_b32_e32 v119, v0
	v_mov_b32_e32 v72, v0
	v_mov_b32_e32 v73, v0
	v_mov_b32_e32 v74, v0
	v_mov_b32_e32 v75, v0
	v_mov_b32_e32 v76, v0
	v_mov_b32_e32 v77, v0
	v_mov_b32_e32 v78, v0
	v_mov_b32_e32 v79, v0
	v_mov_b32_e32 v88, v0
	v_mov_b32_e32 v89, v0
	v_mov_b32_e32 v90, v0
	v_mov_b32_e32 v91, v0
	v_mov_b32_e32 v92, v0
	v_mov_b32_e32 v93, v0
	v_mov_b32_e32 v94, v0
	v_mov_b32_e32 v95, v0
	v_mov_b32_e32 v104, v0
	v_mov_b32_e32 v105, v0
	v_mov_b32_e32 v106, v0
	v_mov_b32_e32 v107, v0
	v_mov_b32_e32 v108, v0
	v_mov_b32_e32 v109, v0
	v_mov_b32_e32 v110, v0
	v_mov_b32_e32 v111, v0
	v_mov_b32_e32 v120, v0
	v_mov_b32_e32 v121, v0
	v_mov_b32_e32 v122, v0
	v_mov_b32_e32 v123, v0
	v_mov_b32_e32 v124, v0
	v_mov_b32_e32 v125, v0
	v_mov_b32_e32 v126, v0
	v_mov_b32_e32 v127, v0
	.p2align 6

.LBB0_1020:
	s_add_u32 s39, s22, 0x100
	v_mov_b32_e32 v0, 0
	s_addc_u32 s60, s23, 0
	s_mov_b32 s61, -2
	s_waitcnt lgkmcnt(0)
	v_mov_b32_e32 v1, v0
	v_mov_b32_e32 v2, v0
	v_mov_b32_e32 v3, v0
	v_mov_b32_e32 v4, v0
	v_mov_b32_e32 v5, v0
	v_mov_b32_e32 v6, v0
	v_mov_b32_e32 v7, v0
	v_mov_b32_e32 v16, v0
	v_mov_b32_e32 v17, v0
	v_mov_b32_e32 v18, v0
	v_mov_b32_e32 v19, v0
	v_mov_b32_e32 v20, v0
	v_mov_b32_e32 v21, v0
	v_mov_b32_e32 v22, v0
	v_mov_b32_e32 v23, v0
	v_mov_b32_e32 v32, v0
	v_mov_b32_e32 v33, v0
	v_mov_b32_e32 v34, v0
	v_mov_b32_e32 v35, v0
	v_mov_b32_e32 v36, v0
	v_mov_b32_e32 v37, v0
	v_mov_b32_e32 v38, v0
	v_mov_b32_e32 v39, v0
	v_mov_b32_e32 v48, v0
	v_mov_b32_e32 v49, v0
	v_mov_b32_e32 v50, v0
	v_mov_b32_e32 v51, v0
	v_mov_b32_e32 v52, v0
	v_mov_b32_e32 v53, v0
	v_mov_b32_e32 v54, v0
	v_mov_b32_e32 v55, v0
	v_mov_b32_e32 v8, v0
	v_mov_b32_e32 v9, v0
	v_mov_b32_e32 v10, v0
	v_mov_b32_e32 v11, v0
	v_mov_b32_e32 v12, v0
	v_mov_b32_e32 v13, v0
	v_mov_b32_e32 v14, v0
	v_mov_b32_e32 v15, v0
	v_mov_b32_e32 v24, v0
	v_mov_b32_e32 v25, v0
	v_mov_b32_e32 v26, v0
	v_mov_b32_e32 v27, v0
	v_mov_b32_e32 v28, v0
	v_mov_b32_e32 v29, v0
	v_mov_b32_e32 v30, v0
	v_mov_b32_e32 v31, v0
	v_mov_b32_e32 v40, v0
	v_mov_b32_e32 v41, v0
	v_mov_b32_e32 v42, v0
	v_mov_b32_e32 v43, v0
	v_mov_b32_e32 v44, v0
	v_mov_b32_e32 v45, v0
	v_mov_b32_e32 v46, v0
	v_mov_b32_e32 v47, v0
	v_mov_b32_e32 v56, v0
	v_mov_b32_e32 v57, v0
	v_mov_b32_e32 v58, v0
	v_mov_b32_e32 v59, v0
	v_mov_b32_e32 v60, v0
	v_mov_b32_e32 v61, v0
	v_mov_b32_e32 v62, v0
	v_mov_b32_e32 v63, v0
	v_mov_b32_e32 v64, v0
	v_mov_b32_e32 v65, v0
	v_mov_b32_e32 v66, v0
	v_mov_b32_e32 v67, v0
	v_mov_b32_e32 v68, v0
	v_mov_b32_e32 v69, v0
	v_mov_b32_e32 v70, v0
	v_mov_b32_e32 v71, v0
	v_mov_b32_e32 v80, v0
	v_mov_b32_e32 v81, v0
	v_mov_b32_e32 v82, v0
	v_mov_b32_e32 v83, v0
	v_mov_b32_e32 v84, v0
	v_mov_b32_e32 v85, v0
	v_mov_b32_e32 v86, v0
	v_mov_b32_e32 v87, v0
	v_mov_b32_e32 v96, v0
	v_mov_b32_e32 v97, v0
	v_mov_b32_e32 v98, v0
	v_mov_b32_e32 v99, v0
	v_mov_b32_e32 v100, v0
	v_mov_b32_e32 v101, v0
	v_mov_b32_e32 v102, v0
	v_mov_b32_e32 v103, v0
	v_mov_b32_e32 v112, v0
	v_mov_b32_e32 v113, v0
	v_mov_b32_e32 v114, v0
	v_mov_b32_e32 v115, v0
	v_mov_b32_e32 v116, v0
	v_mov_b32_e32 v117, v0
	v_mov_b32_e32 v118, v0
	v_mov_b32_e32 v119, v0
	v_mov_b32_e32 v72, v0
	v_mov_b32_e32 v73, v0
	v_mov_b32_e32 v74, v0
	v_mov_b32_e32 v75, v0
	v_mov_b32_e32 v76, v0
	v_mov_b32_e32 v77, v0
	v_mov_b32_e32 v78, v0
	v_mov_b32_e32 v79, v0
	v_mov_b32_e32 v88, v0
	v_mov_b32_e32 v89, v0
	v_mov_b32_e32 v90, v0
	v_mov_b32_e32 v91, v0
	v_mov_b32_e32 v92, v0
	v_mov_b32_e32 v93, v0
	v_mov_b32_e32 v94, v0
	v_mov_b32_e32 v95, v0
	v_mov_b32_e32 v104, v0
	v_mov_b32_e32 v105, v0
	v_mov_b32_e32 v106, v0
	v_mov_b32_e32 v107, v0
	v_mov_b32_e32 v108, v0
	v_mov_b32_e32 v109, v0
	v_mov_b32_e32 v110, v0
	v_mov_b32_e32 v111, v0
	v_mov_b32_e32 v120, v0
	v_mov_b32_e32 v121, v0
	v_mov_b32_e32 v122, v0
	v_mov_b32_e32 v123, v0
	v_mov_b32_e32 v124, v0
	v_mov_b32_e32 v125, v0
	v_mov_b32_e32 v126, v0
	v_mov_b32_e32 v127, v0
	.p2align 6
